# SwiGLU GEMM: units on the peeled entry start accumulator chains from inline 0 (no 128 v_mov zeroing)
# speedup vs baseline: 1.0097x; 1.0006x over previous
; template <class Epi, class Sched, bool ALIGN_EPI = false, bool SP2 = false>
; __device__ __forceinline__ void gemm_phase(PG8_LAS unsigned char* lds, const Gemm g, const Sched& S, const Epi& E, const int tid_in) {
;     ...
; #pragma unroll
;         for (int a = 0; a < 2; ++a)
; #pragma unroll
;             for (int b = 0; b < 2; ++b)
; #pragma unroll
;                 for (int m = 0; m < 4; ++m)
; #pragma unroll
;                     for (int n = 0; n < 2; ++n) acc[a][b][m][n] = (f32x4){0.f, 0.f, 0.f, 0.f};
.LBB0_103:
	s_add_i32 s59, s16, -2
	s_add_u32 s28, s28, 0x40080
	s_addc_u32 s29, s29, 0
	s_add_u32 s60, s34, 0x100
	s_addc_u32 s61, s35, 0
	s_mov_b32 s34, 0
	s_cmp_eq_u32 s93, 1
	s_cbranch_scc1 .Lpeel_104
	v_mov_b32_e32 v2, 0
	v_mov_b32_e32 v3, v2
	v_mov_b32_e32 v4, v2
	v_mov_b32_e32 v5, v2
	v_mov_b32_e32 v10, v2
	v_mov_b32_e32 v11, v2
	v_mov_b32_e32 v12, v2
	v_mov_b32_e32 v13, v2
	v_mov_b32_e32 v18, v2
	v_mov_b32_e32 v19, v2
	v_mov_b32_e32 v20, v2
	v_mov_b32_e32 v21, v2
	v_mov_b32_e32 v26, v2
	v_mov_b32_e32 v27, v2
	v_mov_b32_e32 v28, v2
	v_mov_b32_e32 v29, v2
	v_mov_b32_e32 v34, v2
	v_mov_b32_e32 v35, v2
	v_mov_b32_e32 v36, v2
	v_mov_b32_e32 v37, v2
	v_mov_b32_e32 v42, v2
	v_mov_b32_e32 v43, v2
	v_mov_b32_e32 v44, v2
	v_mov_b32_e32 v45, v2
	v_mov_b32_e32 v50, v2
	v_mov_b32_e32 v51, v2
	v_mov_b32_e32 v52, v2
	v_mov_b32_e32 v53, v2
	v_mov_b32_e32 v58, v2
	v_mov_b32_e32 v59, v2
	v_mov_b32_e32 v60, v2
	v_mov_b32_e32 v61, v2
	v_mov_b32_e32 v6, v2
	v_mov_b32_e32 v7, v2
	v_mov_b32_e32 v8, v2
	v_mov_b32_e32 v9, v2
	v_mov_b32_e32 v14, v2
	v_mov_b32_e32 v15, v2
	v_mov_b32_e32 v16, v2
	v_mov_b32_e32 v17, v2
	v_mov_b32_e32 v22, v2
	v_mov_b32_e32 v23, v2
	v_mov_b32_e32 v24, v2
	v_mov_b32_e32 v25, v2
	v_mov_b32_e32 v30, v2
	v_mov_b32_e32 v31, v2
	v_mov_b32_e32 v32, v2
	v_mov_b32_e32 v33, v2
	v_mov_b32_e32 v38, v2
	v_mov_b32_e32 v39, v2
	v_mov_b32_e32 v40, v2
	v_mov_b32_e32 v41, v2
	v_mov_b32_e32 v46, v2
	v_mov_b32_e32 v47, v2
	v_mov_b32_e32 v48, v2
	v_mov_b32_e32 v49, v2
	v_mov_b32_e32 v54, v2
	v_mov_b32_e32 v55, v2
	v_mov_b32_e32 v56, v2
	v_mov_b32_e32 v57, v2
	v_mov_b32_e32 v62, v2
	v_mov_b32_e32 v63, v2
	v_mov_b32_e32 v64, v2
	v_mov_b32_e32 v65, v2
	v_mov_b32_e32 v66, v2
	v_mov_b32_e32 v67, v2
	v_mov_b32_e32 v68, v2
	v_mov_b32_e32 v69, v2
	v_mov_b32_e32 v74, v2
	v_mov_b32_e32 v75, v2
	v_mov_b32_e32 v76, v2
	v_mov_b32_e32 v77, v2
	v_mov_b32_e32 v82, v2
	v_mov_b32_e32 v83, v2
	v_mov_b32_e32 v84, v2
	v_mov_b32_e32 v85, v2
	v_mov_b32_e32 v90, v2
	v_mov_b32_e32 v91, v2
	v_mov_b32_e32 v92, v2
	v_mov_b32_e32 v93, v2
	v_mov_b32_e32 v98, v2
	v_mov_b32_e32 v99, v2
	v_mov_b32_e32 v100, v2
	v_mov_b32_e32 v101, v2
	v_mov_b32_e32 v106, v2
	v_mov_b32_e32 v107, v2
	v_mov_b32_e32 v108, v2
	v_mov_b32_e32 v109, v2
	v_mov_b32_e32 v114, v2
	v_mov_b32_e32 v115, v2
	v_mov_b32_e32 v116, v2
	v_mov_b32_e32 v117, v2
	v_mov_b32_e32 v122, v2
	v_mov_b32_e32 v123, v2
	v_mov_b32_e32 v124, v2
	v_mov_b32_e32 v125, v2
	v_mov_b32_e32 v70, v2
	v_mov_b32_e32 v71, v2
	v_mov_b32_e32 v72, v2
	v_mov_b32_e32 v73, v2
	v_mov_b32_e32 v78, v2
	v_mov_b32_e32 v79, v2
	v_mov_b32_e32 v80, v2
	v_mov_b32_e32 v81, v2
	v_mov_b32_e32 v86, v2
	v_mov_b32_e32 v87, v2
	v_mov_b32_e32 v88, v2
	v_mov_b32_e32 v89, v2
	v_mov_b32_e32 v94, v2
	v_mov_b32_e32 v95, v2
	v_mov_b32_e32 v96, v2
	v_mov_b32_e32 v97, v2
	v_mov_b32_e32 v102, v2
	v_mov_b32_e32 v103, v2
	v_mov_b32_e32 v104, v2
	v_mov_b32_e32 v105, v2
	v_mov_b32_e32 v110, v2
	v_mov_b32_e32 v111, v2
	v_mov_b32_e32 v112, v2
	v_mov_b32_e32 v113, v2
	v_mov_b32_e32 v118, v2
	v_mov_b32_e32 v119, v2
	v_mov_b32_e32 v120, v2
	v_mov_b32_e32 v121, v2
	v_mov_b32_e32 v126, v2
	v_mov_b32_e32 v127, v2
	v_mov_b32_e32 v128, v2
	v_mov_b32_e32 v129, v2
	s_branch .LBB0_104
; #define PG8_STAGE(bufoff, gbase, voff) do { _Pragma("unroll") for (int _i = 0; _i < 2; ++_i) \
;         __builtin_amdgcn_global_load_lds((const unsigned*)((const char*)(gbase) + (voff)[_i]), (PG8_LAS unsigned*)(lds + (bufoff) + ldsw + _i * 8192), 16, 0, 0); } while (0)
; #define PG8_LDA(dst, b, h) do { _Pragma("unroll") for (int m = 0; m < 4; ++m) _Pragma("unroll") for (int k = 0; k < 2; ++k) dst[m][k] = *(const PG8_LAS bf16x8*)(lds + PG8_SA(b, h) + aoff + m * 2048 + k * 1024); } while (0)
; #define PG8_LDB(dst, b, h) do { _Pragma("unroll") for (int n = 0; n < 2; ++n) _Pragma("unroll") for (int k = 0; k < 2; ++k) dst[n][k] = *(const PG8_LAS bf16x8*)(lds + PG8_SB(b, h) + boff + n * 2048 + k * 1024); } while (0)
; #define PG8_WAIT_V(n) asm volatile("s_waitcnt vmcnt(" #n ")" ::: "memory")
; #define PG8_WAIT_L(n) asm volatile("s_waitcnt lgkmcnt(" #n ")" ::: "memory")
; #define PG8_BAR __builtin_amdgcn_s_barrier()
; #define PG8_SCHED __builtin_amdgcn_sched_barrier(0)
; template <class Epi, class Sched, bool ALIGN_EPI = false, bool SP2 = false>
; __device__ __forceinline__ void gemm_phase(PG8_LAS unsigned char* lds, const Gemm g, const Sched& S, const Epi& E, const int tid_in) {
;     ...
;             PG8_LDB(B0, 0, 0); PG8_LDB(B1, 0, 1); PG8_SCHED; PG8_LDA(At, 0, 0); PG8_STAGE(PG8_SA(1, 1), a1 + hstep, voffA);
;             PG8_WAIT_V(8); PG8_WAIT_L(0); PG8_BAR; PG8_MMA(0, 0, At, B0); PG8_MMA(0, 1, At, B1); PG8_BAR; PG8_SCHED;
;             PG8_LDA(At, 0, 1); PG8_STAGE(PG8_SB(0, 0), b2, voffB); PG8_STAGE(PG8_SB(0, 1), b2 + hstep, voffB); PG8_STAGE(PG8_SA(0, 0), a2, voffA);
;             PG8_WAIT_V(8); PG8_WAIT_L(0); PG8_BAR; PG8_MMA(1, 0, At, B0); PG8_MMA(1, 1, At, B1); PG8_BAR; PG8_SCHED;
.Lpeel_104:
	s_add_i32 s62, s34, 2
	s_add_u32 s35, s28, 0xfffc0080
	s_addc_u32 s40, s29, -1
	s_add_i32 s63, 0, 0x10000
	s_cmp_eq_u32 s59, s34
	s_cselect_b32 s41, s21, s40
	s_cselect_b32 s40, s20, s35
	v_add_u32_e32 v145, s63, v143
	s_cselect_b32 s35, s27, s61
	s_cselect_b32 s34, s26, s60
	s_add_i32 s66, 0, 0x14000
	ds_read_b128 v[146:149], v145
	ds_read_b128 v[150:153], v145 offset:1024
	ds_read_b128 v[154:157], v145 offset:2048
	ds_read_b128 v[158:161], v145 offset:3072
	v_add_u32_e32 v145, s66, v143
	ds_read_b128 v[162:165], v145
	ds_read_b128 v[166:169], v145 offset:1024
	ds_read_b128 v[170:173], v145 offset:2048
	ds_read_b128 v[174:177], v145 offset:3072
	v_lshl_add_u64 v[218:219], s[28:29], 0, v[138:139]
	s_add_i32 m0, s45, 0xc000
	ds_read_b128 v[178:181], v144
	ds_read_b128 v[182:185], v144 offset:1024
	ds_read_b128 v[186:189], v144 offset:2048
	ds_read_b128 v[192:195], v144 offset:3072
	ds_read_b128 v[196:199], v144 offset:4096
	ds_read_b128 v[200:203], v144 offset:5120
	ds_read_b128 v[230:233], v144 offset:6144
	ds_read_b128 v[234:237], v144 offset:7168
	global_load_lds_dwordx4 v[218:219], off
	v_lshl_add_u64 v[218:219], s[28:29], 0, v[140:141]
	s_add_i32 m0, s45, 0xe000
	s_nop 0
	global_load_lds_dwordx4 v[218:219], off
	s_waitcnt vmcnt(16)
	s_waitcnt lgkmcnt(0)
	s_barrier
	s_setprio 1
	s_waitcnt lgkmcnt(0)
	v_mfma_f32_16x16x32_f16 v[126:129], v[146:149], v[178:181], 0
	v_mfma_f32_16x16x32_f16 v[118:121], v[154:157], v[178:181], 0
	v_mfma_f32_16x16x32_f16 v[110:113], v[146:149], v[186:189], 0
	v_mfma_f32_16x16x32_f16 v[102:105], v[154:157], v[186:189], 0
	v_mfma_f32_16x16x32_f16 v[94:97], v[146:149], v[196:199], 0
	v_mfma_f32_16x16x32_f16 v[86:89], v[154:157], v[196:199], 0
	v_mfma_f32_16x16x32_f16 v[78:81], v[146:149], v[230:233], 0
	v_mfma_f32_16x16x32_f16 v[70:73], v[154:157], v[230:233], 0
	v_mfma_f32_16x16x32_f16 v[126:129], v[150:153], v[182:185], v[126:129]
	v_mfma_f32_16x16x32_f16 v[118:121], v[158:161], v[182:185], v[118:121]
	v_mfma_f32_16x16x32_f16 v[110:113], v[150:153], v[192:195], v[110:113]
	v_mfma_f32_16x16x32_f16 v[102:105], v[158:161], v[192:195], v[102:105]
	v_mfma_f32_16x16x32_f16 v[94:97], v[150:153], v[200:203], v[94:97]
	v_mfma_f32_16x16x32_f16 v[86:89], v[158:161], v[200:203], v[86:89]
	v_mfma_f32_16x16x32_f16 v[78:81], v[150:153], v[234:237], v[78:81]
	v_mfma_f32_16x16x32_f16 v[70:73], v[158:161], v[234:237], v[70:73]
	s_setprio 0
	s_setprio 1
	v_mfma_f32_16x16x32_f16 v[122:125], v[162:165], v[178:181], 0
	v_mfma_f32_16x16x32_f16 v[114:117], v[170:173], v[178:181], 0
	v_mfma_f32_16x16x32_f16 v[106:109], v[162:165], v[186:189], 0
	v_mfma_f32_16x16x32_f16 v[98:101], v[170:173], v[186:189], 0
	v_mfma_f32_16x16x32_f16 v[90:93], v[162:165], v[196:199], 0
	v_mfma_f32_16x16x32_f16 v[82:85], v[170:173], v[196:199], 0
	v_mfma_f32_16x16x32_f16 v[74:77], v[162:165], v[230:233], 0
	v_mfma_f32_16x16x32_f16 v[66:69], v[170:173], v[230:233], 0
	v_mfma_f32_16x16x32_f16 v[122:125], v[166:169], v[182:185], v[122:125]
	v_mfma_f32_16x16x32_f16 v[114:117], v[174:177], v[182:185], v[114:117]
	v_mfma_f32_16x16x32_f16 v[106:109], v[166:169], v[192:195], v[106:109]
	v_mfma_f32_16x16x32_f16 v[98:101], v[174:177], v[192:195], v[98:101]
	v_mfma_f32_16x16x32_f16 v[90:93], v[166:169], v[200:203], v[90:93]
	v_mfma_f32_16x16x32_f16 v[82:85], v[174:177], v[200:203], v[82:85]
	v_mfma_f32_16x16x32_f16 v[74:77], v[166:169], v[234:237], v[74:77]
	v_mfma_f32_16x16x32_f16 v[66:69], v[174:177], v[234:237], v[66:69]
	s_setprio 0
	s_barrier
	s_add_i32 s63, s63, s44
	v_lshl_add_u64 v[218:219], s[34:35], 0, v[132:133]
	s_mov_b32 m0, s63
	ds_read_b128 v[178:181], v144 offset:16384
	ds_read_b128 v[182:185], v144 offset:17408
	ds_read_b128 v[186:189], v144 offset:18432
	ds_read_b128 v[192:195], v144 offset:19456
	ds_read_b128 v[196:199], v144 offset:20480
	ds_read_b128 v[200:203], v144 offset:21504
	ds_read_b128 v[230:233], v144 offset:22528
	ds_read_b128 v[234:237], v144 offset:23552
	global_load_lds_dwordx4 v[218:219], off
	s_add_i32 m0, s63, 0x2000
	s_add_u32 s64, s34, 0x40000
	v_lshl_add_u64 v[220:221], s[34:35], 0, v[136:137]
	s_addc_u32 s65, s35, 0
	s_add_i32 s63, s66, s44
	global_load_lds_dwordx4 v[220:221], off
	v_lshl_add_u64 v[222:223], s[64:65], 0, v[132:133]
	s_mov_b32 m0, s63
	v_lshl_add_u64 v[224:225], s[40:41], 0, v[134:135]
	global_load_lds_dwordx4 v[222:223], off
	v_lshl_add_u64 v[222:223], s[64:65], 0, v[136:137]
	s_add_i32 m0, s63, 0x2000
	s_nop 0
	global_load_lds_dwordx4 v[222:223], off
	v_lshl_add_u64 v[222:223], s[40:41], 0, v[130:131]
	s_mov_b32 m0, s45
	s_nop 0
	global_load_lds_dwordx4 v[222:223], off
	s_mov_b32 m0, s47
	s_nop 0
	global_load_lds_dwordx4 v[224:225], off
	s_waitcnt vmcnt(16)
	s_waitcnt lgkmcnt(0)
	s_barrier
	s_setprio 1
	s_waitcnt lgkmcnt(0)
	v_mfma_f32_16x16x32_f16 v[62:65], v[146:149], v[178:181], 0
	v_mfma_f32_16x16x32_f16 v[54:57], v[154:157], v[178:181], 0
	v_mfma_f32_16x16x32_f16 v[46:49], v[146:149], v[186:189], 0
	v_mfma_f32_16x16x32_f16 v[38:41], v[154:157], v[186:189], 0
	v_mfma_f32_16x16x32_f16 v[30:33], v[146:149], v[196:199], 0
	v_mfma_f32_16x16x32_f16 v[22:25], v[154:157], v[196:199], 0
	v_mfma_f32_16x16x32_f16 v[14:17], v[146:149], v[230:233], 0
	v_mfma_f32_16x16x32_f16 v[6:9], v[154:157], v[230:233], 0
	v_mfma_f32_16x16x32_f16 v[62:65], v[150:153], v[182:185], v[62:65]
	v_mfma_f32_16x16x32_f16 v[54:57], v[158:161], v[182:185], v[54:57]
	v_mfma_f32_16x16x32_f16 v[46:49], v[150:153], v[192:195], v[46:49]
	v_mfma_f32_16x16x32_f16 v[38:41], v[158:161], v[192:195], v[38:41]
	v_mfma_f32_16x16x32_f16 v[30:33], v[150:153], v[200:203], v[30:33]
	v_mfma_f32_16x16x32_f16 v[22:25], v[158:161], v[200:203], v[22:25]
	v_mfma_f32_16x16x32_f16 v[14:17], v[150:153], v[234:237], v[14:17]
	v_mfma_f32_16x16x32_f16 v[6:9], v[158:161], v[234:237], v[6:9]
	s_setprio 0
	s_setprio 1
	v_mfma_f32_16x16x32_f16 v[58:61], v[162:165], v[178:181], 0
	v_mfma_f32_16x16x32_f16 v[50:53], v[170:173], v[178:181], 0
	v_mfma_f32_16x16x32_f16 v[42:45], v[162:165], v[186:189], 0
	v_mfma_f32_16x16x32_f16 v[34:37], v[170:173], v[186:189], 0
	v_mfma_f32_16x16x32_f16 v[26:29], v[162:165], v[196:199], 0
	v_mfma_f32_16x16x32_f16 v[18:21], v[170:173], v[196:199], 0
	v_mfma_f32_16x16x32_f16 v[10:13], v[162:165], v[230:233], 0
	v_mfma_f32_16x16x32_f16 v[2:5], v[170:173], v[230:233], 0
	v_mfma_f32_16x16x32_f16 v[58:61], v[166:169], v[182:185], v[58:61]
	v_mfma_f32_16x16x32_f16 v[50:53], v[174:177], v[182:185], v[50:53]
	v_mfma_f32_16x16x32_f16 v[42:45], v[166:169], v[192:195], v[42:45]
	v_mfma_f32_16x16x32_f16 v[34:37], v[174:177], v[192:195], v[34:37]
	v_mfma_f32_16x16x32_f16 v[26:29], v[166:169], v[200:203], v[26:29]
	v_mfma_f32_16x16x32_f16 v[18:21], v[174:177], v[200:203], v[18:21]
	v_mfma_f32_16x16x32_f16 v[10:13], v[166:169], v[234:237], v[10:13]
	v_mfma_f32_16x16x32_f16 v[2:5], v[174:177], v[234:237], v[2:5]
	s_setprio 0
	s_barrier
	s_branch .Lmid_104
